# fused LN: gamma/beta loads issued before the last statistics barrier instead of after it
# baseline (speedup 1.0000x reference)
; template <unsigned D> __device__ __forceinline__ u32x4 rd8(u32x4 w) { w.x = rd<D>(w.x); w.y = rd<D>(w.y); w.z = rd<D>(w.z); w.w = rd<D>(w.w); return w; }
; __device__ __forceinline__ u32x4 pk8(const f32x4 v0, const f32x4 v1) { u32x4 w; w.x = pk_f16(v0[0], v0[1]); w.y = pk_f16(v0[2], v0[3]); w.z = pk_f16(v1[0], v1[1]); w.w = pk_f16(v1[2], v1[3]); return w; }
; __device__ __forceinline__ unsigned pk4_fp8(float a, float b, float c, float d) { int w = __builtin_amdgcn_cvt_pk_fp8_f32(a, b, 0, false); w = __builtin_amdgcn_cvt_pk_fp8_f32(c, d, w, true); return (unsigned)w; }
;     __device__ __forceinline__ void fused(f32x4 (&acc)[2][2][4][2], const GUnit& u, int wr, int wc, int fr, int fq, LAS unsigned char* lds, int wid, int lane) const {
;     ...
;         asm volatile("s_waitcnt lgkmcnt(0)" ::: "memory"); __builtin_amdgcn_s_barrier(); asm volatile("" ::: "memory");
;         const float qnan = __builtin_nanf("");
;         f32x4 gv[2][2], bv[2][2];
; #pragma unroll
;         for (int bj = 0; bj < 2; ++bj)
; #pragma unroll
;             for (int n = 0; n < 2; ++n) { gv[bj][n] = *(const f32x4*)(ln_g + gcol0 + bj * 128 + 4 * n); bv[bj][n] = *(const f32x4*)(ln_b + gcol0 + bj * 128 + 4 * n); }
; #pragma unroll
;         for (int ai = 0; ai < 2; ++ai)
; #pragma unroll
;             for (int m = 0; m < 4; ++m) { const int r = ai * 128 + wr * 64 + m * 16 + fr; const f32x2 sr = S[r]; const size_t row = (size_t)(u.pm * 256 + r);
; #pragma unroll
;                 for (int bj = 0; bj < 2; ++bj) { const int col = gcol0 + bj * 128;
;                     f32x4 y0 = (acc[ai][bj][m][0] - sr.x) * sr.y * gv[bj][0] + bv[bj][0], y1 = (acc[ai][bj][m][1] - sr.x) * sr.y * gv[bj][1] + bv[bj][1];
;                     if (bad) { y0 = (f32x4){qnan, qnan, qnan, qnan}; y1 = y0; }
;                     if (last) { *(f32x4*)(out + row * 1024 + col) = y0; *(f32x4*)(out + row * 1024 + col + 4) = y1; }
;                     else { *(u32x4*)(H16 + row * 1024 + col) = rd8<D_H>(pk8(y0, y1));
;                            if (h8out) { u32x2 q8v; q8v.x = pk4_fp8(y0[0], y0[1], y0[2], y0[3]); q8v.y = pk4_fp8(y1[0], y1[1], y1[2], y1[3]); *(u32x2*)(ws + WS_H8 + row * 1024 + col) = q8v; } } }
.LBB0_470:
	s_or_b64 exec, exec, s[2:3]
	s_lshl_b32 s4, s72, 12
	v_readlane_b32 s2, v255, 9
	v_readlane_b32 s3, v255, 10
	s_add_u32 s2, s2, s4
	s_addc_u32 s3, s3, 0
	v_readlane_b32 s6, v255, 11
	v_readlane_b32 s7, v255, 12
	s_add_u32 s4, s6, s4
	s_addc_u32 s5, s7, 0
	v_lshlrev_b64 v[132:133], 2, v[198:199]
	v_lshl_add_u64 v[136:137], s[2:3], 0, v[132:133]
	v_lshl_add_u64 v[144:145], s[4:5], 0, v[132:133]
	global_load_dwordx4 v[156:159], v[144:145], off
	global_load_dwordx4 v[160:163], v[136:137], off
	global_load_dwordx4 v[148:151], v[136:137], off offset:16
	global_load_dwordx4 v[152:155], v[144:145], off offset:16
	s_waitcnt lgkmcnt(1)
	global_load_dwordx4 v[132:135], v[136:137], off offset:528
	global_load_dwordx4 v[140:143], v[136:137], off offset:512
	s_nop 0
	global_load_dwordx4 v[136:139], v[144:145], off offset:528
	s_nop 0
	global_load_dwordx4 v[144:147], v[144:145], off offset:512
	s_waitcnt lgkmcnt(0)
	s_barrier
	v_lshl_add_u32 v32, v233, 3, 0
	ds_read_b64 v[168:169], v32 offset:8192
	v_readlane_b32 s2, v253, 4
	v_readlane_b32 s3, v253, 5
	s_cmp_lg_u32 s72, 3
	s_mov_b64 s[6:7], -1
	s_waitcnt lgkmcnt(0)
	v_cmp_eq_u32_e64 s[100:101], 0, v170
	s_nop 1
	v_cndmask_b32_e64 v169, v229, v169, s[100:101]
	v_pk_add_f32 v[172:173], v[130:131], v[168:169] op_sel_hi:[1,0] neg_lo:[0,1] neg_hi:[0,1]
	v_pk_add_f32 v[130:131], v[126:127], v[168:169] op_sel_hi:[1,0] neg_lo:[0,1] neg_hi:[0,1]
	v_pk_add_f32 v[174:175], v[128:129], v[168:169] op_sel_hi:[1,0] neg_lo:[0,1] neg_hi:[0,1]
	v_pk_add_f32 v[128:129], v[124:125], v[168:169] op_sel_hi:[1,0] neg_lo:[0,1] neg_hi:[0,1]
	v_pk_mul_f32 v[126:127], v[168:169], v[172:173] op_sel:[1,0]
	v_pk_mul_f32 v[124:125], v[168:169], v[174:175] op_sel:[1,0]
	v_pk_mul_f32 v[130:131], v[168:169], v[130:131] op_sel:[1,0]
	v_pk_mul_f32 v[128:129], v[168:169], v[128:129] op_sel:[1,0]
	v_lshl_add_u64 v[166:167], s[2:3], 0, v[216:217]
	s_cselect_b64 s[2:3], -1, 0
	s_xor_b64 s[4:5], s[26:27], -1
	s_or_b64 s[2:3], s[2:3], s[4:5]
	v_cmp_eq_u32_e64 s[4:5], 0, v170
	v_lshlrev_b64 v[164:165], 10, v[214:215]
	v_lshl_add_u64 v[166:167], v[198:199], 1, v[166:167]
	s_and_b64 vcc, exec, s[2:3]
	s_waitcnt vmcnt(6)
	v_pk_fma_f32 v[126:127], v[162:163], v[126:127], v[158:159]
	v_pk_fma_f32 v[124:125], v[160:161], v[124:125], v[156:157]
	s_waitcnt vmcnt(4)
	v_pk_fma_f32 v[130:131], v[150:151], v[130:131], v[154:155]
	v_pk_fma_f32 v[128:129], v[148:149], v[128:129], v[152:153]
	s_cbranch_vccz .LBB0_474
	v_cvt_pk_f16_f32 v170, v124, v125
	v_cvt_pk_f16_f32 v171, v126, v127
	v_cvt_pk_f16_f32 v172, v128, v129
	v_cvt_pk_f16_f32 v173, v130, v131
	v_add_u32_e32 v170, 0x20002, v170
	v_add_u32_e32 v171, 0x20002, v171
	v_add_u32_e32 v172, 0x20002, v172
	v_add_u32_e32 v173, 0x20002, v173
	v_and_b32_e32 v170, 0xfffcfffc, v170
	v_and_b32_e32 v171, 0xfffcfffc, v171
	v_and_b32_e32 v172, 0xfffcfffc, v172
	v_and_b32_e32 v173, 0xfffcfffc, v173
	s_and_b64 vcc, exec, s[16:17]
	global_store_dwordx4 v[166:167], v[170:173], off
	s_cbranch_vccnz .LBB0_473
	s_nop 0
	v_mov_b32_e32 v170, v33
	v_mov_b32_e32 v171, v33
	v_cvt_pk_fp8_f32 v170, v124, v125
	v_cvt_pk_fp8_f32 v171, v128, v129
	v_readlane_b32 s6, v252, 26
	v_readlane_b32 s7, v252, 27
	v_cvt_pk_fp8_f32 v170, v126, v127 op_sel:[0,0,1]
	v_cvt_pk_fp8_f32 v171, v130, v131 op_sel:[0,0,1]
	v_lshl_add_u64 v[172:173], s[6:7], 0, v[164:165]
	v_lshl_add_u64 v[172:173], v[172:173], 0, v[198:199]
	global_store_dwordx2 v[172:173], v[170:171], off
